# sample-conv unit: LayerNorm+swish of its 4 tokens on 4 waves (one token each) instead of 2 waves x 2 sequential tokens
# baseline (speedup 1.0000x reference)
; #define LAS __attribute__((address_space(3)))
;     bf16_t* CACT = WSP(bf16_t, WS_CACT);
;     unsigned ln = (unsigned)F.lane; asm volatile("" : "+v"(ln));
; #pragma unroll
;     for (int tt = 0; tt < 2; ++tt) { const int t = 2 * F.wave + tt; if (t >= ntok) break;
;         f32x4 y[6]; float s = 0.f;
; #pragma unroll
;         for (int k = 0; k < 6; ++k) { y[k] = *(const LAS f32x4*)(Y + t * DCONV + 256 * k + 4 * ln); s += (y[k][0] + y[k][1]) + (y[k][2] + y[k][3]); }
;         const float mean = wave_sum(s) * (1.0f / DCONV); float qq = 0.f;
; #pragma unroll
;         for (int k = 0; k < 6; ++k) { y[k] = y[k] - mean; qq += (y[k][0] * y[k][0] + y[k][1] * y[k][1]) + (y[k][2] * y[k][2] + y[k][3] * y[k][3]); }
;         const float rstd = 1.0f / sqrtf(wave_sum(qq) * (1.0f / DCONV) + EPS);
; __device__ __forceinline__ void p2_mixers(LAS unsigned char* lds, const ConvW& cw) {
;     ...
;     { Frame F = make_frame(lds); for (int bs = (F.vcu + F.G - 64) % F.G; bs < DB; bs += F.G) p2_conv_unit_sample(F, bs, cw); }
.LBB0_446:
	s_mov_b32 s99, s8
	s_abs_i32 s29, s3
	v_cvt_f32_u32_e32 v1, s29
	s_add_i32 s8, s3, s8
	s_sub_i32 s9, s8, 64
	s_sub_i32 s8, 64, s8
	v_rcp_iflag_f32_e32 v1, v1
	s_ashr_i32 s40, s9, 31
	s_max_i32 s8, s9, s8
	s_sub_i32 s9, 0, s29
	v_mul_f32_e32 v1, 0x4f7ffffe, v1
	v_cvt_u32_f32_e32 v1, v1
	s_mov_b64 s[6:7], s[0:1]
	v_readfirstlane_b32 s44, v1
	s_mul_i32 s9, s9, s44
	s_mul_hi_u32 s9, s44, s9
	s_add_i32 s44, s44, s9
	s_mul_hi_u32 s9, s8, s44
	s_mul_i32 s9, s9, s29
	s_sub_i32 s8, s8, s9
	s_sub_i32 s9, s8, s29
	s_cmp_ge_u32 s8, s29
	s_cselect_b32 s8, s9, s8
	s_sub_i32 s9, s8, s29
	s_cmp_ge_u32 s8, s29
	s_cselect_b32 s8, s9, s8
	s_xor_b32 s41, s8, s40
	s_sub_i32 s22, s41, s40
	s_lshr_b32 s22, s99, 2
	s_lshl_b32 s22, s22, 1
	s_and_b32 s100, s99, 1
	s_or_b32 s22, s22, s100
	s_bitcmp1_b32 s99, 1
	s_cselect_b32 s22, 0xff, s22
	s_mov_b32 s41, s22
	s_mov_b32 s40, 0
	s_cmpk_gt_i32 s22, 0x7f
	s_cbranch_scc1 .LBB0_452
	s_load_dwordx2 s[18:19], s[6:7], 0x30
	s_load_dwordx4 s[8:11], s[6:7], 0x80
	s_ashr_i32 s36, s12, 6
	s_load_dwordx2 s[6:7], s[6:7], 0xb0
	s_mul_i32 s23, s36, 0xc0
	s_add_i32 s24, s23, 0x80
	v_and_b32_e32 v134, 63, v2
	v_lshl_add_u32 v135, v134, 1, s23
	s_waitcnt lgkmcnt(0)
	s_add_u32 s25, s6, 0x5e00000
	s_addc_u32 s26, s7, 0
	s_add_u32 s27, s6, 0xd200000
	s_addc_u32 s34, s7, 0
	s_cmp_lt_i32 s36, 4
	s_cselect_b64 s[12:13], -1, 0
	s_mov_b32 s35, s36
	s_or_b32 s37, s35, 1
	s_cmp_lt_i32 s37, 0
	s_mul_i32 s7, s22, 0x2d000
	s_cselect_b64 s[16:17], -1, 0
	s_mul_hi_i32 s6, s22, 0x2d000
	s_add_u32 s7, s18, s7
	s_addc_u32 s6, s19, s6
	s_add_u32 s18, s7, 0x2b800
	s_addc_u32 s19, s6, 0
	s_lshl_b32 s6, s41, 2
	s_lshl_b32 s7, s40, 2
	s_sub_i32 s6, s6, s7
	v_or_b32_e32 v136, s24, v134
	s_mulk_i32 s36, 0x1800
	s_mulk_i32 s37, 0x1800
	s_mul_hi_i32 s38, s3, 0x2d000
	s_mul_i32 s39, s3, 0x2d000
	s_add_i32 s40, s6, 0x2003
	s_lshl_b32 s41, s3, 2
	v_mov_b32_e32 v33, 0
	v_mov_b32_e32 v137, 0x358637bd
	s_mov_b32 s42, 0xf800000
	v_mov_b32_e32 v138, 0x260
	v_mov_b32_e32 v139, 0xba2aaaab
	v_mov_b32_e32 v140, 0x3a2aaaab
	s_branch .LBB0_449
